# RG-LRU gate loops: waves 4-7 delayed by s_sleep 12 (~768 clk) at loop entry so the two waves of a SIMD alternate MFMA and VALU sections
# speedup vs baseline: 1.0078x; 1.0014x over previous
; #define LAS __attribute__((address_space(3)))
; __device__ __forceinline__ unsigned cvt_pk_bf16(float lo, float hi) { unsigned r; asm volatile("v_cvt_pk_bf16_f32 %0, %1, %2" : "=v"(r) : "v"(lo), "v"(hi)); return r; }
; __device__ __forceinline__ float bflo(unsigned w) { return __uint_as_float(w << 16); }
; __device__ __forceinline__ float bfhi(unsigned w) { return __uint_as_float(w & 0xffff0000u); }
; __device__ __forceinline__ int lru_perm(int t) { return (t & ~63) | ((t & 12) << 2) | ((t & 48) >> 2) | (t & 3); }
; template <bool PASS2>
; __device__ __forceinline__ void lru_item(const Frame& F, const Args& a, int item) {
;     ...
; #pragma unroll 2
;         for (int it = 0; it < 8; ++it) { const int tl = r0 + 32 * it;
;             f32x4 x0 = cbv[0], x1 = cbv[1];
; #pragma unroll
;             for (int j = 0; j < 4; ++j) { const u32x4 v = *(const LAS u32x4*)(R0 + (tl + j) * AT_PITCH + 16 * cch);
;                 x0[0] += cw[j][0][0] * bflo(v.x); x0[1] += cw[j][0][1] * bfhi(v.x); x0[2] += cw[j][0][2] * bflo(v.y); x0[3] += cw[j][0][3] * bfhi(v.y);
;                 x1[0] += cw[j][1][0] * bflo(v.z); x1[1] += cw[j][1][1] * bfhi(v.z); x1[2] += cw[j][1][2] * bflo(v.w); x1[3] += cw[j][1][3] * bfhi(v.w); }
;             u32x4 o; o.x = cvt_pk_bf16(x0[0], x0[1]); o.y = cvt_pk_bf16(x0[2], x0[3]); o.z = cvt_pk_bf16(x1[0], x1[1]); o.w = cvt_pk_bf16(x1[2], x1[3]);
;             *(LAS u32x4*)(AT + lru_perm(tl) * AT_PITCH + 16 * cch) = o; }
.LBB0_148:
	v_add_u32_e32 v84, s5, v113
	ds_read_b128 v[46:49], v84
	ds_read_b128 v[50:53], v84 offset:272
	ds_read_b128 v[54:57], v84 offset:544
	ds_read_b128 v[58:61], v84 offset:816
	v_and_or_b32 v62, v45, s49, v111
	v_add_u32_e32 v64, 32, v45
	v_mad_u64_u32 v[62:63], s[6:7], v62, s45, v[100:101]
	v_and_b32_e32 v65, 12, v44
	v_and_b32_e32 v63, 0xfffffc3, v64
	s_waitcnt lgkmcnt(2)
	v_lshlrev_b32_e32 v67, 16, v50
	v_lshlrev_b32_e32 v66, 16, v46
	v_and_b32_e32 v69, 0xffff0000, v50
	v_and_b32_e32 v68, 0xffff0000, v46
	v_or3_b32 v63, v63, v65, v109
	v_lshlrev_b32_e32 v71, 16, v51
	v_lshlrev_b32_e32 v70, 16, v47
	v_and_b32_e32 v51, 0xffff0000, v51
	v_and_b32_e32 v50, 0xffff0000, v47
	v_lshlrev_b32_e32 v47, 16, v52
	v_lshlrev_b32_e32 v46, 16, v48
	v_and_b32_e32 v73, 0xffff0000, v52
	v_and_b32_e32 v72, 0xffff0000, v48
	v_lshlrev_b32_e32 v75, 16, v53
	v_lshlrev_b32_e32 v74, 16, v49
	v_and_b32_e32 v53, 0xffff0000, v53
	v_and_b32_e32 v52, 0xffff0000, v49
	s_waitcnt lgkmcnt(0)
	v_lshlrev_b32_e32 v49, 16, v58
	v_lshlrev_b32_e32 v48, 16, v54
	v_and_b32_e32 v77, 0xffff0000, v58
	v_and_b32_e32 v76, 0xffff0000, v54
	v_lshlrev_b32_e32 v78, 16, v55
	v_and_b32_e32 v58, 0xffff0000, v55
	v_lshlrev_b32_e32 v55, 16, v60
	v_lshlrev_b32_e32 v54, 16, v56
	v_and_b32_e32 v81, 0xffff0000, v60
	v_and_b32_e32 v80, 0xffff0000, v56
	v_lshlrev_b32_e32 v82, 16, v57
	v_and_b32_e32 v60, 0xffff0000, v57
	v_pk_mul_f32 v[56:57], v[34:35], v[66:67]
	v_pk_mul_f32 v[66:67], v[4:5], v[68:69]
	v_mad_u64_u32 v[64:65], s[6:7], v63, s45, v[100:101]
	v_pk_mul_f32 v[68:69], v[32:33], v[70:71]
	v_pk_mul_f32 v[50:51], v[6:7], v[50:51]
	v_pk_mul_f32 v[46:47], v[30:31], v[46:47]
	v_pk_mul_f32 v[70:71], v[8:9], v[72:73]
	v_pk_mul_f32 v[72:73], v[28:29], v[74:75]
	v_pk_mul_f32 v[52:53], v[10:11], v[52:53]
	s_waitcnt vmcnt(1)
	v_add_f32_e32 v56, v20, v56
	v_add_f32_e32 v63, v21, v66
	v_lshlrev_b32_e32 v79, 16, v59
	v_and_b32_e32 v59, 0xffff0000, v59
	v_lshlrev_b32_e32 v83, 16, v61
	v_and_b32_e32 v61, 0xffff0000, v61
	v_pk_mul_f32 v[48:49], v[42:43], v[48:49]
	v_pk_mul_f32 v[74:75], v[16:17], v[76:77]
	v_add_f32_e32 v65, v22, v68
	v_add_f32_e32 v50, v23, v50
	s_waitcnt vmcnt(0)
	v_add_f32_e32 v46, v24, v46
	v_add_f32_e32 v66, v25, v70
	v_add_f32_e32 v68, v26, v72
	v_add_f32_e32 v52, v27, v52
	v_add_f32_e32 v56, v56, v57
	v_add_f32_e32 v57, v63, v67
	v_pk_mul_f32 v[76:77], v[40:41], v[78:79]
	v_pk_mul_f32 v[58:59], v[18:19], v[58:59]
	v_pk_mul_f32 v[54:55], v[38:39], v[54:55]
	v_pk_mul_f32 v[78:79], v[12:13], v[80:81]
	v_pk_mul_f32 v[80:81], v[36:37], v[82:83]
	v_pk_mul_f32 v[60:61], v[14:15], v[60:61]
	v_add_f32_e32 v63, v65, v69
	v_add_f32_e32 v50, v50, v51
	v_add_f32_e32 v46, v46, v47
	v_add_f32_e32 v47, v66, v71
	v_add_f32_e32 v51, v68, v73
	v_add_f32_e32 v52, v52, v53
	v_add_f32_e32 v48, v56, v48
	v_add_f32_e32 v53, v57, v74
	v_add_f32_e32 v56, v63, v76
	v_add_f32_e32 v50, v50, v58
	v_add_f32_e32 v46, v46, v54
	v_add_f32_e32 v47, v47, v78
	v_add_f32_e32 v51, v51, v80
	v_add_f32_e32 v52, v52, v60
	v_add_f32_e32 v48, v48, v49
	v_add_f32_e32 v49, v53, v75
	v_add_f32_e32 v53, v56, v77
	v_add_f32_e32 v50, v50, v59
	v_add_f32_e32 v54, v46, v55
	v_add_f32_e32 v55, v47, v79
	v_add_f32_e32 v51, v51, v81
	v_add_f32_e32 v52, v52, v61
	v_cvt_pk_bf16_f32 v46, v48, v49
	v_cvt_pk_bf16_f32 v47, v53, v50
	v_cvt_pk_bf16_f32 v48, v54, v55
	v_cvt_pk_bf16_f32 v49, v51, v52
	ds_write_b128 v62, v[46:49]
	ds_read_b128 v[46:49], v84 offset:8976
	ds_read_b128 v[50:53], v84 offset:8704
	ds_read_b128 v[54:57], v84 offset:9248
	ds_read_b128 v[58:61], v84 offset:9520
	s_addk_i32 s5, 0x4400
	s_waitcnt lgkmcnt(3)
	v_lshlrev_b32_e32 v63, 16, v46
	s_waitcnt lgkmcnt(2)
	v_lshlrev_b32_e32 v62, 16, v50
	v_and_b32_e32 v67, 0xffff0000, v46
	v_and_b32_e32 v66, 0xffff0000, v50
	v_lshlrev_b32_e32 v69, 16, v47
	v_lshlrev_b32_e32 v68, 16, v51
	v_and_b32_e32 v47, 0xffff0000, v47
	v_and_b32_e32 v46, 0xffff0000, v51
	v_lshlrev_b32_e32 v51, 16, v48
	v_lshlrev_b32_e32 v50, 16, v52
	v_and_b32_e32 v71, 0xffff0000, v48
	v_and_b32_e32 v70, 0xffff0000, v52
	v_lshlrev_b32_e32 v73, 16, v49
	v_lshlrev_b32_e32 v72, 16, v53
	v_and_b32_e32 v49, 0xffff0000, v49
	v_and_b32_e32 v48, 0xffff0000, v53
	s_waitcnt lgkmcnt(0)
	v_lshlrev_b32_e32 v53, 16, v58
	v_lshlrev_b32_e32 v52, 16, v54
	v_and_b32_e32 v75, 0xffff0000, v58
	v_and_b32_e32 v74, 0xffff0000, v54
	v_lshlrev_b32_e32 v76, 16, v55
	v_and_b32_e32 v58, 0xffff0000, v55
	v_lshlrev_b32_e32 v55, 16, v60
	v_lshlrev_b32_e32 v54, 16, v56
	v_and_b32_e32 v79, 0xffff0000, v60
	v_and_b32_e32 v78, 0xffff0000, v56
	v_lshlrev_b32_e32 v80, 16, v57
	v_and_b32_e32 v60, 0xffff0000, v57
	v_pk_mul_f32 v[56:57], v[34:35], v[62:63]
	v_pk_mul_f32 v[62:63], v[4:5], v[66:67]
	v_pk_mul_f32 v[66:67], v[32:33], v[68:69]
	v_pk_mul_f32 v[46:47], v[6:7], v[46:47]
	v_pk_mul_f32 v[50:51], v[30:31], v[50:51]
	v_pk_mul_f32 v[68:69], v[8:9], v[70:71]
	v_pk_mul_f32 v[70:71], v[28:29], v[72:73]
	v_pk_mul_f32 v[48:49], v[10:11], v[48:49]
	v_add_f32_e32 v56, v20, v56
	v_lshlrev_b32_e32 v77, 16, v59
	v_and_b32_e32 v59, 0xffff0000, v59
	v_lshlrev_b32_e32 v81, 16, v61
	v_and_b32_e32 v61, 0xffff0000, v61
	v_pk_mul_f32 v[52:53], v[42:43], v[52:53]
	v_add_f32_e32 v62, v21, v62
	v_add_f32_e32 v65, v22, v66
	v_add_f32_e32 v46, v23, v46
	v_add_f32_e32 v50, v24, v50
	v_add_f32_e32 v66, v25, v68
	v_add_f32_e32 v68, v26, v70
	v_add_f32_e32 v48, v27, v48
	v_add_f32_e32 v56, v56, v57
	v_pk_mul_f32 v[72:73], v[16:17], v[74:75]
	v_pk_mul_f32 v[74:75], v[40:41], v[76:77]
	v_pk_mul_f32 v[58:59], v[18:19], v[58:59]
	v_pk_mul_f32 v[54:55], v[38:39], v[54:55]
	v_pk_mul_f32 v[76:77], v[12:13], v[78:79]
	v_pk_mul_f32 v[78:79], v[36:37], v[80:81]
	v_pk_mul_f32 v[60:61], v[14:15], v[60:61]
	v_add_f32_e32 v57, v62, v63
	v_add_f32_e32 v62, v65, v67
	v_add_f32_e32 v46, v46, v47
	v_add_f32_e32 v47, v50, v51
	v_add_f32_e32 v50, v66, v69
	v_add_f32_e32 v51, v68, v71
	v_add_f32_e32 v48, v48, v49
	v_add_f32_e32 v49, v56, v52
	v_add_u32_e32 v45, 64, v45
	v_add_u32_e32 v44, 16, v44
	s_cmp_eq_u32 s5, 0x11000
	v_add_f32_e32 v52, v57, v72
	v_add_f32_e32 v56, v62, v74
	v_add_f32_e32 v46, v46, v58
	v_add_f32_e32 v47, v47, v54
	v_add_f32_e32 v50, v50, v76
	v_add_f32_e32 v51, v51, v78
	v_add_f32_e32 v48, v48, v60
	v_add_f32_e32 v49, v49, v53
	v_add_f32_e32 v52, v52, v73
	v_add_f32_e32 v53, v56, v75
	v_add_f32_e32 v54, v46, v59
	v_add_f32_e32 v55, v47, v55
	v_add_f32_e32 v50, v50, v77
	v_add_f32_e32 v51, v51, v79
	v_add_f32_e32 v56, v48, v61
	v_cvt_pk_bf16_f32 v46, v49, v52
	v_cvt_pk_bf16_f32 v47, v53, v54
	v_cvt_pk_bf16_f32 v48, v55, v50
	v_cvt_pk_bf16_f32 v49, v51, v56
	ds_write_b128 v64, v[46:49]
	s_cbranch_scc0 .LBB0_148
; template <bool PASS2>
; __device__ __forceinline__ void lru_item(const Frame& F, const Args& a, int item) {
;     ...
;         const bf16_t* wt = (const bf16_t*)(a.ws + WS_WLRU) + (size_t)((dir * 12 + n) * 2) * 16384 + (size_t)c * 128 + 8 * fq;
;         bf16x8 wrf[4], wif[4];
; #pragma unroll
;         for (int ks = 0; ks < 4; ++ks) { wrf[ks] = *(const bf16x8*)(wt + 32 * ks); wif[ks] = *(const bf16x8*)(wt + 16384 + 32 * ks); }
;         const float ba = a.lru_ba[dir * 1536 + cg_], bi = a.lru_bi[dir * 1536 + cg_];
;         const float lam = a.lru_lambda[dir * 1536 + cg_];
;         const float logu = -8.0f * log1pf(__expf(-lam));
;         float hc = 0.f, TA = 1.f, TB = 0.f;
;         if (PASS2) { const f32x2* ag = (const f32x2*)(a.ws + WS_AGG) + ((size_t)(b * NCHUNK) * 2 + dir) * 1536 + cg_;
;             f32x2 pa[NCHUNK];
; #pragma unroll
;             for (int cc = 0; cc < NCHUNK; ++cc) pa[cc] = ag[(size_t)cc * 2 * 1536];
; #pragma unroll
;             for (int i = 0; i < NCHUNK; ++i) { const int cc = dir ? NCHUNK - 1 - i : i; const bool use = dir ? (cc > chunk) : (cc < chunk); if (use) hc = pa[cc].x * hc + pa[cc].y; } }
;         const int tstart = dir ? SEQ - 1 : 0;
;         if (dir == 1) __syncthreads();
; #pragma unroll 1
;         for (int si = 0; si < 4; ++si) { const int s = dir ? 3 - si : si;
	v_add_u32_e32 v104, s4, v92
	v_ashrrev_i32_e32 v105, 31, v104
	v_readlane_b32 s60, v242, 17
	v_lshlrev_b64 v[4:5], 2, v[104:105]
	v_readlane_b32 s61, v242, 18
	s_waitcnt lgkmcnt(0)
	s_barrier
	v_lshl_add_u64 v[6:7], s[60:61], 0, v[4:5]
	s_waitcnt vmcnt(0)
	v_mov_b32_e32 v26, v178
	s_lshl_b32 s40, s13, 1
	s_ashr_i32 s41, s40, 31
	s_lshl_b64 s[4:5], s[40:41], 15
	v_lshl_add_u64 v[20:21], v[102:103], 0, s[4:5]
	v_lshl_add_u64 v[22:23], s[86:87], 0, v[4:5]
	v_lshl_add_u64 v[24:25], s[90:91], 0, v[4:5]
	v_add_co_u32_e32 v32, vcc, 0x8000, v20
	v_mov_b32_e32 v4, v146
	v_mov_b32_e32 v5, v147
	v_mov_b32_e32 v6, v148
	v_mov_b32_e32 v7, v149
	v_mov_b32_e32 v8, v150
	v_mov_b32_e32 v9, v151
	v_mov_b32_e32 v10, v152
	v_mov_b32_e32 v11, v153
	v_mov_b32_e32 v12, v154
	v_mov_b32_e32 v13, v155
	v_mov_b32_e32 v14, v156
	v_mov_b32_e32 v15, v157
	v_mov_b32_e32 v16, v158
	v_mov_b32_e32 v17, v159
	v_mov_b32_e32 v18, v160
	v_mov_b32_e32 v19, v161
	v_mov_b32_e32 v128, v179
	v_mov_b32_e32 v130, v180
	v_addc_co_u32_e32 v33, vcc, 0, v21, vcc
	s_mov_b32 s39, 0
	v_mov_b32_e32 v106, 1.0
	v_or_b32_e32 v124, 64, v122
	v_or_b32_e32 v125, 0x80, v122
	v_or_b32_e32 v126, 0xc0, v122
	v_add_u32_e32 v127, s57, v93
	v_mov_b32_e32 v129, 0
	v_mov_b32_e32 v132, v116
	v_readlane_b32 s62, v242, 19
	v_readlane_b32 s63, v242, 20
	v_readlane_b32 s64, v242, 21
	v_readlane_b32 s65, v242, 22
	v_readlane_b32 s66, v242, 23
	v_readlane_b32 s67, v242, 24
	v_readlane_b32 s68, v242, 25
	v_readlane_b32 s69, v242, 26
	v_readlane_b32 s70, v242, 27
	v_readlane_b32 s71, v242, 28
	v_readlane_b32 s72, v242, 29
	v_readlane_b32 s73, v242, 30
	v_readlane_b32 s74, v242, 31
	v_readlane_b32 s75, v242, 32
	s_waitcnt vmcnt(6)
	v_mul_f32_e32 v20, 0xbfb8aa3b, v26
	v_exp_f32_e32 v38, v20
	v_mov_b32_e32 v20, v162
	v_mov_b32_e32 v21, v163
	v_mov_b32_e32 v22, v164
	v_mov_b32_e32 v23, v165
	v_mov_b32_e32 v24, v166
	v_mov_b32_e32 v25, v167
	v_mov_b32_e32 v26, v168
	v_mov_b32_e32 v27, v169
	v_mov_b32_e32 v28, v170
	v_mov_b32_e32 v29, v171
	v_mov_b32_e32 v30, v172
	v_mov_b32_e32 v31, v173
	s_nop 0
	v_mov_b32_e32 v32, v174
	v_mov_b32_e32 v33, v175
	v_mov_b32_e32 v34, v176
	v_mov_b32_e32 v35, v177
	v_add_f32_e32 v39, 1.0, v38
	v_add_f32_e32 v40, -1.0, v39
	v_frexp_mant_f32_e32 v41, v39
	v_cvt_f64_f32_e32 v[36:37], v39
	v_sub_f32_e32 v42, v40, v39
	v_frexp_exp_i32_f64_e32 v36, v[36:37]
	v_cmp_gt_f32_e32 vcc, s50, v41
	v_sub_f32_e32 v40, v38, v40
	v_add_f32_e32 v37, 1.0, v42
	v_subbrev_co_u32_e32 v36, vcc, 0, v36, vcc
	v_add_f32_e32 v37, v40, v37
	v_sub_u32_e32 v40, 0, v36
	v_cvt_f32_i32_e32 v36, v36
	v_ldexp_f32 v39, v39, v40
	v_ldexp_f32 v37, v37, v40
	v_add_f32_e32 v40, -1.0, v39
	v_add_f32_e32 v41, 1.0, v39
	v_add_f32_e32 v42, 1.0, v40
	v_add_f32_e32 v43, -1.0, v41
	v_sub_f32_e32 v42, v39, v42
	v_sub_f32_e32 v39, v39, v43
	v_mul_f32_e32 v43, 0x3f317218, v36
	v_add_f32_e32 v42, v37, v42
	v_add_f32_e32 v37, v37, v39
	v_fma_f32 v39, v36, s51, -v43
	v_add_f32_e32 v44, v40, v42
	v_add_f32_e32 v45, v41, v37
	v_fmac_f32_e32 v39, 0xb102e308, v36
	v_sub_f32_e32 v36, v44, v40
	v_sub_f32_e32 v40, v45, v41
	v_rcp_f32_e32 v41, v45
	v_add_f32_e32 v46, v43, v39
	v_sub_f32_e32 v37, v37, v40
	v_sub_f32_e32 v40, v46, v43
	v_sub_f32_e32 v39, v39, v40
	v_mul_f32_e32 v40, v44, v41
	v_sub_f32_e32 v36, v42, v36
	v_mul_f32_e32 v42, v45, v40
	v_fma_f32 v43, v40, v45, -v42
	v_fmac_f32_e32 v43, v40, v37
	v_add_f32_e32 v47, v42, v43
	v_sub_f32_e32 v48, v44, v47
	v_sub_f32_e32 v42, v47, v42
	v_sub_f32_e32 v44, v44, v48
	v_sub_f32_e32 v42, v42, v43
	v_sub_f32_e32 v43, v44, v47
	v_add_f32_e32 v36, v36, v43
	v_add_f32_e32 v36, v42, v36
	v_add_f32_e32 v42, v48, v36
	v_mul_f32_e32 v43, v41, v42
	v_sub_f32_e32 v44, v48, v42
	v_mul_f32_e32 v47, v45, v43
	v_add_f32_e32 v36, v36, v44
	v_add_f32_e32 v44, v40, v43
	v_fma_f32 v45, v43, v45, -v47
	v_sub_f32_e32 v40, v44, v40
	v_fmac_f32_e32 v45, v43, v37
	v_sub_f32_e32 v37, v43, v40
	v_add_f32_e32 v40, v47, v45
	v_sub_f32_e32 v43, v40, v47
	v_sub_f32_e32 v47, v42, v40
	v_sub_f32_e32 v42, v42, v47
	v_sub_f32_e32 v40, v42, v40
	v_sub_f32_e32 v43, v43, v45
	v_add_f32_e32 v36, v36, v40
	v_add_f32_e32 v36, v43, v36
	v_add_f32_e32 v36, v47, v36
	v_mul_f32_e32 v36, v41, v36
	v_add_f32_e32 v36, v37, v36
	v_add_f32_e32 v37, v44, v36
	v_mul_f32_e32 v40, v37, v37
	v_fmamk_f32 v43, v40, 0x3e9b6dac, v117
	v_sub_f32_e32 v41, v37, v44
	v_ldexp_f32 v42, v37, 1
	v_mul_f32_e32 v37, v37, v40
	v_fmaak_f32 v40, v40, v43, 0x3f2aaada
	v_mul_f32_e32 v37, v37, v40
	v_add_f32_e32 v40, v42, v37
	v_sub_f32_e32 v36, v36, v41
	v_sub_f32_e32 v41, v40, v42
	v_ldexp_f32 v36, v36, 1
	v_sub_f32_e32 v37, v37, v41
	v_add_f32_e32 v36, v36, v37
	v_add_f32_e32 v37, v40, v36
	v_sub_f32_e32 v40, v37, v40
	v_add_f32_e32 v41, v46, v37
	v_sub_f32_e32 v36, v36, v40
	v_sub_f32_e32 v40, v41, v46
	v_sub_f32_e32 v42, v41, v40
	v_sub_f32_e32 v37, v37, v40
	v_add_f32_e32 v40, v39, v36
	v_sub_f32_e32 v42, v46, v42
	v_sub_f32_e32 v43, v40, v39
	v_add_f32_e32 v37, v37, v42
	v_sub_f32_e32 v42, v40, v43
	v_sub_f32_e32 v36, v36, v43
	v_sub_f32_e32 v39, v39, v42
	v_add_f32_e32 v37, v40, v37
	v_add_f32_e32 v36, v36, v39
	v_add_f32_e32 v39, v41, v37
	v_sub_f32_e32 v40, v39, v41
	v_sub_f32_e32 v37, v37, v40
	v_add_f32_e32 v36, v36, v37
	v_add_f32_e32 v36, v39, v36
	v_cmp_neq_f32_e32 vcc, s52, v38
	s_nop 1
	v_cndmask_b32_e32 v36, v119, v36, vcc
	v_cmp_ngt_f32_e32 vcc, -1.0, v38
	s_nop 1
	v_cndmask_b32_e32 v36, v120, v36, vcc
	v_cmp_neq_f32_e32 vcc, -1.0, v38
	s_nop 1
	v_cndmask_b32_e32 v36, v121, v36, vcc
	v_cmp_lt_f32_e64 vcc, |v38|, s53
	s_nop 1
	v_cndmask_b32_e32 v36, v36, v38, vcc
	v_mul_f32_e32 v131, 0xc1000000, v36
	v_readfirstlane_b32 s98, v144
	s_cmp_lt_u32 s98, 0x100
	s_cbranch_scc1 .Lstag_150
	s_sleep 12
.Lstag_150:
.LBB0_150:
	v_mul_f32_e32 v191, 0x3fb8aa3b, v131
	s_mov_b32 s100, 0xbfb8aa3b
	v_mul_f32_e32 v181, 0xbfb8aa3b, v128
	v_mul_f32_e32 v190, 0xbfb8aa3b, v130
	v_add_u32_e32 v107, v132, v93
	v_add_u32_e32 v193, 0x11400, v107
	ds_read_b128 v[194:197], v193
	ds_read_b128 v[198:201], v193 offset:64
	ds_read_b128 v[202:205], v193 offset:128
	ds_read_b128 v[206:209], v193 offset:192
	ds_read_b128 v[210:213], v193 offset:4352
	ds_read_b128 v[214:217], v193 offset:4416
	ds_read_b128 v[218:221], v193 offset:4480
	ds_read_b128 v[222:225], v193 offset:4544
	ds_read_b128 v[226:229], v193 offset:8704
	ds_read_b128 v[248:251], v193 offset:8768
	ds_read_b128 v[252:255], v193 offset:8832
	v_cndmask_b32_e64 v40, 0, 1, s[2:3]
	v_cmp_ne_u32_e64 s[10:11], 1, v40
	s_mov_b32 s14, s12
	s_mov_b32 s15, s12
	s_mov_b32 s13, s12
	v_mov_b64_e32 v[66:67], s[14:15]
	v_mov_b64_e32 v[64:65], s[12:13]
	s_andn2_b64 vcc, exec, s[2:3]
	s_waitcnt vmcnt(9) lgkmcnt(10)
	v_mfma_f32_16x16x32_bf16 v[44:47], v[194:197], v[4:7], 0
	s_waitcnt vmcnt(3)
	v_mfma_f32_16x16x32_bf16 v[40:43], v[194:197], v[20:23], 0
	s_cbranch_vccnz .LBB0_152
	v_mfma_f32_16x16x32_bf16 v[64:67], v[194:197], v[0:3], 0

; template <bool PASS2>
; __device__ __forceinline__ void lru_item(const Frame& F, const Args& a, int item) {
;     ...
;         const bf16_t* wt = (const bf16_t*)(a.ws + WS_WLRU) + (size_t)((dir * 12 + n) * 2) * 16384 + (size_t)c * 128 + 8 * fq;
;         bf16x8 wrf[4], wif[4];
; #pragma unroll
;         for (int ks = 0; ks < 4; ++ks) { wrf[ks] = *(const bf16x8*)(wt + 32 * ks); wif[ks] = *(const bf16x8*)(wt + 16384 + 32 * ks); }
;         const float ba = a.lru_ba[dir * 1536 + cg_], bi = a.lru_bi[dir * 1536 + cg_];
;         const float lam = a.lru_lambda[dir * 1536 + cg_];
;         const float logu = -8.0f * log1pf(__expf(-lam));
;         float hc = 0.f, TA = 1.f, TB = 0.f;
;         if (PASS2) { const f32x2* ag = (const f32x2*)(a.ws + WS_AGG) + ((size_t)(b * NCHUNK) * 2 + dir) * 1536 + cg_;
;             f32x2 pa[NCHUNK];
; #pragma unroll
;             for (int cc = 0; cc < NCHUNK; ++cc) pa[cc] = ag[(size_t)cc * 2 * 1536];
; #pragma unroll
;             for (int i = 0; i < NCHUNK; ++i) { const int cc = dir ? NCHUNK - 1 - i : i; const bool use = dir ? (cc > chunk) : (cc < chunk); if (use) hc = pa[cc].x * hc + pa[cc].y; } }
;         const int tstart = dir ? SEQ - 1 : 0;
;         if (dir == 1) __syncthreads();
; #pragma unroll 1
;         for (int si = 0; si < 4; ++si) { const int s = dir ? 3 - si : si;
.LBB0_186:
	s_or_b64 exec, exec, s[14:15]
	v_add_u32_e32 v4, 0x600, v104
	v_mov_b32_e32 v5, v95
	v_readlane_b32 s60, v242, 17
	v_lshlrev_b64 v[4:5], 2, v[4:5]
	v_readlane_b32 s61, v242, 18
	s_add_i32 s14, s40, 24
	s_mov_b32 s15, s12
	v_lshl_add_u64 v[6:7], s[60:61], 0, v[4:5]
	v_mov_b32_e32 v36, v142
	s_lshl_b64 s[14:15], s[14:15], 15
	v_lshl_add_u64 v[20:21], v[102:103], 0, s[14:15]
	v_lshl_add_u64 v[22:23], s[86:87], 0, v[4:5]
	v_lshl_add_u64 v[24:25], s[90:91], 0, v[4:5]
	v_add_co_u32_e32 v32, vcc, 0x8000, v20
	v_mov_b32_e32 v4, v182
	v_mov_b32_e32 v5, v183
	v_mov_b32_e32 v6, v184
	v_mov_b32_e32 v7, v185
	v_mov_b32_e32 v8, v186
	v_mov_b32_e32 v9, v187
	v_mov_b32_e32 v10, v188
	v_mov_b32_e32 v11, v189
	v_mov_b32_e32 v12, v230
	v_mov_b32_e32 v13, v231
	v_mov_b32_e32 v14, v232
	v_mov_b32_e32 v15, v233
	v_mov_b32_e32 v16, v234
	v_mov_b32_e32 v17, v235
	v_mov_b32_e32 v18, v236
	v_mov_b32_e32 v19, v237
	v_mov_b32_e32 v128, v143
	v_mov_b32_e32 v129, v145
	v_addc_co_u32_e32 v33, vcc, 0, v21, vcc
	v_mov_b32_e32 v20, v238
	v_mov_b32_e32 v21, v239
	v_mov_b32_e32 v22, v240
	v_mov_b32_e32 v23, v241
	v_mov_b32_e32 v24, v134
	v_mov_b32_e32 v25, v135
	v_mov_b32_e32 v26, v136
	v_mov_b32_e32 v27, v137
	v_mov_b32_e32 v28, v138
	v_mov_b32_e32 v29, v139
	v_mov_b32_e32 v30, v140
	v_mov_b32_e32 v31, v141
	s_nop 0
	v_mov_b32_e32 v32, v244
	v_mov_b32_e32 v33, v245
	v_mov_b32_e32 v34, v246
	v_mov_b32_e32 v35, v247
	v_or_b32_e32 v127, s57, v93
	s_mov_b32 s39, 0
	v_mov_b32_e32 v106, 1.0
	v_mov_b32_e32 v131, 0
	v_readlane_b32 s62, v242, 19
	v_readlane_b32 s63, v242, 20
	v_readlane_b32 s64, v242, 21
	v_readlane_b32 s65, v242, 22
	v_readlane_b32 s66, v242, 23
	v_readlane_b32 s67, v242, 24
	v_readlane_b32 s68, v242, 25
	v_readlane_b32 s69, v242, 26
	v_readlane_b32 s70, v242, 27
	v_readlane_b32 s71, v242, 28
	v_readlane_b32 s72, v242, 29
	v_readlane_b32 s73, v242, 30
	v_readlane_b32 s74, v242, 31
	v_readlane_b32 s75, v242, 32
	s_barrier
	s_waitcnt vmcnt(10)
	v_mul_f32_e32 v36, 0xbfb8aa3b, v36
	v_exp_f32_e32 v38, v36
	s_nop 0
	v_add_f32_e32 v39, 1.0, v38
	v_add_f32_e32 v40, -1.0, v39
	v_frexp_mant_f32_e32 v41, v39
	v_cvt_f64_f32_e32 v[36:37], v39
	v_sub_f32_e32 v42, v40, v39
	v_frexp_exp_i32_f64_e32 v36, v[36:37]
	v_cmp_gt_f32_e32 vcc, s50, v41
	v_sub_f32_e32 v40, v38, v40
	v_add_f32_e32 v37, 1.0, v42
	v_subbrev_co_u32_e32 v36, vcc, 0, v36, vcc
	v_add_f32_e32 v37, v40, v37
	v_sub_u32_e32 v40, 0, v36
	v_cvt_f32_i32_e32 v36, v36
	v_ldexp_f32 v39, v39, v40
	v_ldexp_f32 v37, v37, v40
	v_add_f32_e32 v40, -1.0, v39
	v_add_f32_e32 v41, 1.0, v39
	v_add_f32_e32 v42, 1.0, v40
	v_add_f32_e32 v43, -1.0, v41
	v_sub_f32_e32 v42, v39, v42
	v_sub_f32_e32 v39, v39, v43
	v_mul_f32_e32 v43, 0x3f317218, v36
	v_add_f32_e32 v42, v37, v42
	v_add_f32_e32 v37, v37, v39
	v_fma_f32 v39, v36, s51, -v43
	v_add_f32_e32 v44, v40, v42
	v_add_f32_e32 v45, v41, v37
	v_fmac_f32_e32 v39, 0xb102e308, v36
	v_sub_f32_e32 v36, v44, v40
	v_sub_f32_e32 v40, v45, v41
	v_rcp_f32_e32 v41, v45
	v_add_f32_e32 v46, v43, v39
	v_sub_f32_e32 v37, v37, v40
	v_sub_f32_e32 v40, v46, v43
	v_sub_f32_e32 v39, v39, v40
	v_mul_f32_e32 v40, v44, v41
	v_sub_f32_e32 v36, v42, v36
	v_mul_f32_e32 v42, v45, v40
	v_fma_f32 v43, v40, v45, -v42
	v_fmac_f32_e32 v43, v40, v37
	v_add_f32_e32 v47, v42, v43
	v_sub_f32_e32 v48, v44, v47
	v_sub_f32_e32 v42, v47, v42
	v_sub_f32_e32 v44, v44, v48
	v_sub_f32_e32 v42, v42, v43
	v_sub_f32_e32 v43, v44, v47
	v_add_f32_e32 v36, v36, v43
	v_add_f32_e32 v36, v42, v36
	v_add_f32_e32 v42, v48, v36
	v_mul_f32_e32 v43, v41, v42
	v_sub_f32_e32 v44, v48, v42
	v_mul_f32_e32 v47, v45, v43
	v_add_f32_e32 v36, v36, v44
	v_add_f32_e32 v44, v40, v43
	v_fma_f32 v45, v43, v45, -v47
	v_sub_f32_e32 v40, v44, v40
	v_fmac_f32_e32 v45, v43, v37
	v_sub_f32_e32 v37, v43, v40
	v_add_f32_e32 v40, v47, v45
	v_sub_f32_e32 v43, v40, v47
	v_sub_f32_e32 v47, v42, v40
	v_sub_f32_e32 v42, v42, v47
	v_sub_f32_e32 v40, v42, v40
	v_sub_f32_e32 v43, v43, v45
	v_add_f32_e32 v36, v36, v40
	v_add_f32_e32 v36, v43, v36
	v_add_f32_e32 v36, v47, v36
	v_mul_f32_e32 v36, v41, v36
	v_add_f32_e32 v36, v37, v36
	v_add_f32_e32 v37, v44, v36
	v_mul_f32_e32 v40, v37, v37
	v_fmamk_f32 v43, v40, 0x3e9b6dac, v117
	v_sub_f32_e32 v41, v37, v44
	v_ldexp_f32 v42, v37, 1
	v_mul_f32_e32 v37, v37, v40
	v_fmaak_f32 v40, v40, v43, 0x3f2aaada
	v_mul_f32_e32 v37, v37, v40
	v_add_f32_e32 v40, v42, v37
	v_sub_f32_e32 v36, v36, v41
	v_sub_f32_e32 v41, v40, v42
	v_ldexp_f32 v36, v36, 1
	v_sub_f32_e32 v37, v37, v41
	v_add_f32_e32 v36, v36, v37
	v_add_f32_e32 v37, v40, v36
	v_sub_f32_e32 v40, v37, v40
	v_add_f32_e32 v41, v46, v37
	v_sub_f32_e32 v36, v36, v40
	v_sub_f32_e32 v40, v41, v46
	v_sub_f32_e32 v42, v41, v40
	v_sub_f32_e32 v37, v37, v40
	v_add_f32_e32 v40, v39, v36
	v_sub_f32_e32 v42, v46, v42
	v_sub_f32_e32 v43, v40, v39
	v_add_f32_e32 v37, v37, v42
	v_sub_f32_e32 v42, v40, v43
	v_sub_f32_e32 v36, v36, v43
	v_sub_f32_e32 v39, v39, v42
	v_add_f32_e32 v37, v40, v37
	v_add_f32_e32 v36, v36, v39
	v_add_f32_e32 v39, v41, v37
	v_sub_f32_e32 v40, v39, v41
	v_sub_f32_e32 v37, v37, v40
	v_add_f32_e32 v36, v36, v37
	v_add_f32_e32 v36, v39, v36
	v_cmp_neq_f32_e32 vcc, s52, v38
	s_nop 1
	v_cndmask_b32_e32 v36, v119, v36, vcc
	v_cmp_ngt_f32_e32 vcc, -1.0, v38
	s_nop 1
	v_cndmask_b32_e32 v36, v120, v36, vcc
	v_cmp_neq_f32_e32 vcc, -1.0, v38
	s_nop 1
	v_cndmask_b32_e32 v36, v121, v36, vcc
	v_cmp_lt_f32_e64 vcc, |v38|, s53
	s_nop 1
	v_cndmask_b32_e32 v36, v36, v38, vcc
	v_mul_f32_e32 v130, 0xc1000000, v36
	v_readfirstlane_b32 s98, v144
	s_cmp_lt_u32 s98, 0x100
	s_cbranch_scc1 .Lstag_187
	s_sleep 12
.Lstag_187:
.LBB0_187:
	v_mul_f32_e32 v191, 0x3fb8aa3b, v130
	s_mov_b32 s100, 0xbfb8aa3b
	v_mul_f32_e32 v181, 0xbfb8aa3b, v128
	v_mul_f32_e32 v190, 0xbfb8aa3b, v129
	v_bitop3_b32 v36, s39, v101, v123 bitop3:0xde
	v_mul_lo_u32 v36, v36, s45
	v_add_u32_e32 v107, v110, v36
	ds_read_b128 v[194:197], v107
	ds_read_b128 v[198:201], v107 offset:64
	ds_read_b128 v[202:205], v107 offset:128
	ds_read_b128 v[206:209], v107 offset:192
	ds_read_b128 v[210:213], v107 offset:4352
	ds_read_b128 v[214:217], v107 offset:4416
	ds_read_b128 v[218:221], v107 offset:4480
	ds_read_b128 v[222:225], v107 offset:4544
	ds_read_b128 v[226:229], v107 offset:8704
	ds_read_b128 v[248:251], v107 offset:8768
	ds_read_b128 v[252:255], v107 offset:8832
	s_mov_b32 s14, s12
	s_mov_b32 s15, s12
	s_mov_b32 s13, s12
	v_mov_b64_e32 v[38:39], s[14:15]
	s_and_b64 vcc, exec, s[10:11]
	v_mov_b64_e32 v[36:37], s[12:13]
	s_waitcnt vmcnt(9) lgkmcnt(10)
	v_mfma_f32_16x16x32_bf16 v[44:47], v[194:197], v[4:7], 0
	s_waitcnt vmcnt(3)
	v_mfma_f32_16x16x32_bf16 v[48:51], v[194:197], v[20:23], 0
	s_cbranch_vccnz .LBB0_189
	v_mfma_f32_16x16x32_bf16 v[36:39], v[194:197], v[0:3], 0

; template <bool PASS2>
; __device__ __forceinline__ void lru_item(const Frame& F, const Args& a, int item) {
;     ...
;         const float ba = a.lru_ba[dir * 1536 + cg_], bi = a.lru_bi[dir * 1536 + cg_];
;         const float lam = a.lru_lambda[dir * 1536 + cg_];
;         const float logu = -8.0f * log1pf(__expf(-lam));
;         float hc = 0.f, TA = 1.f, TB = 0.f;
;         if (PASS2) { const f32x2* ag = (const f32x2*)(a.ws + WS_AGG) + ((size_t)(b * NCHUNK) * 2 + dir) * 1536 + cg_;
;             f32x2 pa[NCHUNK];
; #pragma unroll
;             for (int cc = 0; cc < NCHUNK; ++cc) pa[cc] = ag[(size_t)cc * 2 * 1536];
; #pragma unroll
;             for (int i = 0; i < NCHUNK; ++i) { const int cc = dir ? NCHUNK - 1 - i : i; const bool use = dir ? (cc > chunk) : (cc < chunk); if (use) hc = pa[cc].x * hc + pa[cc].y; } }
;         const int tstart = dir ? SEQ - 1 : 0;
;         if (dir == 1) __syncthreads();
; #pragma unroll 1
;         for (int si = 0; si < 4; ++si) { const int s = dir ? 3 - si : si;
.LBB0_707:
	s_waitcnt vmcnt(15)
	v_mul_f32_e32 v4, 0xbfb8aa3b, v125
	v_exp_f32_e32 v4, v4
	s_mov_b32 s8, 0x3f2aaaab
	s_cmp_gt_i32 s33, 1
	s_waitcnt vmcnt(13)
	v_fmac_f32_e32 v75, v74, v5
	v_add_f32_e32 v8, 1.0, v4
	v_frexp_mant_f32_e32 v10, v8
	v_cvt_f64_f32_e32 v[6:7], v8
	v_add_f32_e32 v9, -1.0, v8
	v_frexp_exp_i32_f64_e32 v6, v[6:7]
	v_cmp_gt_f32_e32 vcc, s8, v10
	v_sub_f32_e32 v11, v9, v8
	v_sub_f32_e32 v9, v4, v9
	v_subbrev_co_u32_e32 v6, vcc, 0, v6, vcc
	v_add_f32_e32 v11, 1.0, v11
	v_sub_u32_e32 v7, 0, v6
	v_add_f32_e32 v9, v9, v11
	v_ldexp_f32 v8, v8, v7
	v_ldexp_f32 v7, v9, v7
	v_add_f32_e32 v9, -1.0, v8
	v_add_f32_e32 v12, 1.0, v8
	v_add_f32_e32 v10, 1.0, v9
	v_add_f32_e32 v13, -1.0, v12
	v_sub_f32_e32 v10, v8, v10
	v_sub_f32_e32 v8, v8, v13
	v_add_f32_e32 v10, v7, v10
	v_add_f32_e32 v7, v7, v8
	v_add_f32_e32 v8, v12, v7
	v_rcp_f32_e32 v13, v8
	v_add_f32_e32 v11, v9, v10
	v_sub_f32_e32 v9, v11, v9
	v_sub_f32_e32 v9, v10, v9
	v_sub_f32_e32 v10, v8, v12
	v_sub_f32_e32 v7, v7, v10
	v_mul_f32_e32 v10, v11, v13
	v_mul_f32_e32 v12, v8, v10
	v_fma_f32 v14, v10, v8, -v12
	v_fmac_f32_e32 v14, v10, v7
	v_add_f32_e32 v15, v12, v14
	v_sub_f32_e32 v16, v11, v15
	v_sub_f32_e32 v11, v11, v16
	v_sub_f32_e32 v12, v15, v12
	v_sub_f32_e32 v11, v11, v15
	v_add_f32_e32 v9, v9, v11
	v_sub_f32_e32 v11, v12, v14
	v_add_f32_e32 v9, v11, v9
	v_add_f32_e32 v11, v16, v9
	v_mul_f32_e32 v12, v13, v11
	v_mul_f32_e32 v14, v8, v12
	v_fma_f32 v8, v12, v8, -v14
	v_fmac_f32_e32 v8, v12, v7
	v_sub_f32_e32 v7, v16, v11
	v_add_f32_e32 v7, v9, v7
	v_add_f32_e32 v9, v14, v8
	v_sub_f32_e32 v15, v11, v9
	v_sub_f32_e32 v11, v11, v15
	v_sub_f32_e32 v14, v9, v14
	v_sub_f32_e32 v9, v11, v9
	v_add_f32_e32 v7, v7, v9
	v_sub_f32_e32 v8, v14, v8
	v_cvt_f32_i32_e32 v6, v6
	v_add_f32_e32 v7, v8, v7
	v_add_f32_e32 v8, v10, v12
	v_add_f32_e32 v7, v15, v7
	v_sub_f32_e32 v9, v8, v10
	v_mul_f32_e32 v7, v13, v7
	v_sub_f32_e32 v9, v12, v9
	v_add_f32_e32 v7, v9, v7
	v_mul_f32_e32 v12, 0x3f317218, v6
	s_mov_b32 s8, 0x3f317218
	v_add_f32_e32 v9, v8, v7
	v_fma_f32 v13, v6, s8, -v12
	v_mul_f32_e32 v10, v9, v9
	v_fmac_f32_e32 v13, 0xb102e308, v6
	v_sub_f32_e32 v6, v9, v8
	v_fmamk_f32 v11, v10, 0x3e9b6dac, v134
	v_sub_f32_e32 v6, v7, v6
	v_add_f32_e32 v7, v12, v13
	v_fmaak_f32 v11, v10, v11, 0x3f2aaada
	v_sub_f32_e32 v8, v7, v12
	v_ldexp_f32 v12, v9, 1
	v_mul_f32_e32 v9, v9, v10
	v_mul_f32_e32 v9, v9, v11
	v_add_f32_e32 v10, v12, v9
	v_sub_f32_e32 v11, v10, v12
	v_ldexp_f32 v6, v6, 1
	v_sub_f32_e32 v9, v9, v11
	v_add_f32_e32 v6, v6, v9
	v_add_f32_e32 v9, v10, v6
	v_sub_f32_e32 v10, v9, v10
	v_sub_f32_e32 v6, v6, v10
	v_add_f32_e32 v10, v7, v9
	v_sub_f32_e32 v11, v10, v7
	v_sub_f32_e32 v12, v10, v11
	v_sub_f32_e32 v8, v13, v8
	v_sub_f32_e32 v7, v7, v12
	v_sub_f32_e32 v9, v9, v11
	v_add_f32_e32 v7, v9, v7
	v_add_f32_e32 v9, v8, v6
	v_sub_f32_e32 v11, v9, v8
	v_sub_f32_e32 v12, v9, v11
	v_sub_f32_e32 v8, v8, v12
	v_sub_f32_e32 v6, v6, v11
	v_add_f32_e32 v7, v9, v7
	v_add_f32_e32 v6, v6, v8
	v_add_f32_e32 v8, v10, v7
	v_sub_f32_e32 v9, v8, v10
	v_sub_f32_e32 v7, v7, v9
	v_add_f32_e32 v6, v6, v7
	s_mov_b32 s8, 0x7f800000
	v_add_f32_e32 v6, v8, v6
	v_cmp_neq_f32_e32 vcc, s8, v4
	s_mov_b32 s8, 0x33800000
	s_mov_b32 s49, 0
	v_cndmask_b32_e32 v6, v137, v6, vcc
	v_cmp_ngt_f32_e32 vcc, -1.0, v4
	v_add_u32_e32 v208, s74, v105
	v_mov_b32_e32 v209, v123
	v_cndmask_b32_e32 v6, v138, v6, vcc
	v_cmp_neq_f32_e32 vcc, -1.0, v4
	v_mov_b32_e32 v205, 0
	v_mov_b32_e32 v203, 0
	v_cndmask_b32_e32 v6, v139, v6, vcc
	v_cmp_lt_f32_e64 vcc, |v4|, s8
	v_mov_b32_e32 v202, 0
	v_mov_b32_e32 v200, 0
	v_cndmask_b32_e32 v4, v6, v4, vcc
	s_cselect_b64 vcc, -1, 0
	v_cndmask_b32_e32 v5, v5, v75, vcc
	s_cmp_gt_i32 s33, 2
	s_waitcnt vmcnt(12)
	v_fmac_f32_e32 v73, v72, v5
	s_cselect_b64 vcc, -1, 0
	v_cndmask_b32_e32 v5, v5, v73, vcc
	s_cmp_gt_i32 s33, 3
	s_waitcnt vmcnt(11)
	v_fmac_f32_e32 v69, v68, v5
	s_cselect_b64 vcc, -1, 0
	v_cndmask_b32_e32 v5, v5, v69, vcc
	s_cmp_gt_i32 s33, 4
	s_waitcnt vmcnt(10)
	v_fmac_f32_e32 v71, v70, v5
	s_cselect_b64 vcc, -1, 0
	v_cndmask_b32_e32 v5, v5, v71, vcc
	s_cmp_gt_i32 s33, 5
	s_waitcnt vmcnt(9)
	v_fmac_f32_e32 v83, v82, v5
	s_cselect_b64 vcc, -1, 0
	v_cndmask_b32_e32 v5, v5, v83, vcc
	s_cmp_gt_i32 s33, 6
	s_waitcnt vmcnt(8)
	v_fmac_f32_e32 v81, v80, v5
	s_cselect_b64 vcc, -1, 0
	v_cndmask_b32_e32 v5, v5, v81, vcc
	s_cmp_gt_i32 s33, 7
	s_waitcnt vmcnt(7)
	v_fmac_f32_e32 v77, v76, v5
	s_cselect_b64 vcc, -1, 0
	v_cndmask_b32_e32 v5, v5, v77, vcc
	s_cmp_gt_i32 s33, 8
	s_waitcnt vmcnt(6)
	v_fmac_f32_e32 v79, v78, v5
	s_cselect_b64 vcc, -1, 0
	v_cndmask_b32_e32 v5, v5, v79, vcc
	s_cmp_gt_i32 s33, 9
	s_waitcnt vmcnt(5)
	v_fmac_f32_e32 v91, v90, v5
	s_cselect_b64 vcc, -1, 0
	v_cndmask_b32_e32 v5, v5, v91, vcc
	s_cmp_gt_i32 s33, 10
	s_waitcnt vmcnt(4)
	v_fmac_f32_e32 v89, v88, v5
	s_cselect_b64 vcc, -1, 0
	v_cndmask_b32_e32 v5, v5, v89, vcc
	s_cmp_gt_i32 s33, 11
	s_waitcnt vmcnt(3)
	v_fmac_f32_e32 v85, v84, v5
	s_cselect_b64 vcc, -1, 0
	v_cndmask_b32_e32 v5, v5, v85, vcc
	s_cmp_gt_i32 s33, 12
	s_waitcnt vmcnt(2)
	v_fmac_f32_e32 v87, v86, v5
	s_cselect_b64 vcc, -1, 0
	v_cndmask_b32_e32 v5, v5, v87, vcc
	s_cmp_gt_i32 s33, 13
	s_waitcnt vmcnt(1)
	v_fmac_f32_e32 v131, v130, v5
	s_cselect_b64 vcc, -1, 0
	v_cndmask_b32_e32 v5, v5, v131, vcc
	s_cmp_gt_i32 s33, 14
	s_waitcnt vmcnt(0)
	v_fmac_f32_e32 v129, v128, v5
	s_cselect_b64 vcc, -1, 0
	v_cndmask_b32_e32 v210, v5, v129, vcc
	v_mul_f32_e32 v207, 0xc1000000, v4
	v_or_b32_e32 v128, 64, v140
	v_or_b32_e32 v129, 0x80, v140
	v_or_b32_e32 v130, 0xc0, v140
	v_mov_b32_e32 v198, 0
	v_mov_b32_e32 v133, 0
	v_mov_b32_e32 v143, 0
	v_mov_b32_e32 v145, 0
	v_mov_b32_e32 v146, 0
	v_mov_b32_e32 v131, 0
	v_mov_b32_e32 v132, 0
	v_mov_b32_e32 v4, 0
	v_mov_b32_e32 v5, 0
	v_mov_b32_e32 v6, 0
	v_mov_b32_e32 v7, 0
	v_mov_b32_e32 v8, 0
	v_mov_b32_e32 v9, 0
	v_mov_b32_e32 v10, 0
	v_mov_b32_e32 v11, 0
	v_mov_b32_e32 v12, 0
	v_mov_b32_e32 v13, 0
	v_mov_b32_e32 v147, 0
	v_mov_b32_e32 v148, 0
	v_mov_b32_e32 v149, 0
	v_mov_b32_e32 v150, 0
	v_mov_b32_e32 v151, 0
	v_mov_b32_e32 v152, 0
	v_mov_b32_e32 v153, 0
	v_mov_b32_e32 v154, 0
	v_mov_b32_e32 v155, 0
	v_mov_b32_e32 v156, 0
	v_mov_b32_e32 v157, 0
	v_mov_b32_e32 v158, 0
	v_mov_b32_e32 v159, 0
	v_mov_b32_e32 v160, 0
	v_mov_b32_e32 v161, 0
	v_mov_b32_e32 v162, 0
	v_mov_b32_e32 v163, 0
	v_mov_b32_e32 v164, 0
	v_mov_b32_e32 v165, 0
	v_mov_b32_e32 v166, 0
	v_mov_b32_e32 v167, 0
	v_mov_b32_e32 v168, 0
	v_mov_b32_e32 v169, 0
	v_mov_b32_e32 v170, 0
	v_mov_b32_e32 v171, 0
	v_mov_b32_e32 v172, 0
	v_readfirstlane_b32 s98, v144
	s_cmp_lt_u32 s98, 0x100
	s_cbranch_scc1 .Lstag_708
	s_sleep 12
; #define LAS __attribute__((address_space(3)))
; template <bool PASS2>
; __device__ __forceinline__ void lru_item(const Frame& F, const Args& a, int item) {
;     ...
;             f32x4 ar[4], ai[4], ax[4];
; #pragma unroll
;             for (int rt = 0; rt < 4; ++rt) { ar[rt] = (f32x4){0.f, 0.f, 0.f, 0.f}; ai[rt] = (f32x4){0.f, 0.f, 0.f, 0.f}; ax[rt] = (f32x4){0.f, 0.f, 0.f, 0.f};
; #pragma unroll
;                 for (int ks = 0; ks < 4; ++ks) { const bf16x8 xf = *(const LAS bf16x8*)(AT + (64 * s + 16 * rt + fr) * AT_PITCH + 64 * ks + 16 * fq);
;                     ar[rt] = __builtin_amdgcn_mfma_f32_16x16x32_bf16(xf, wrf[ks], ar[rt], 0, 0, 0); ai[rt] = __builtin_amdgcn_mfma_f32_16x16x32_bf16(xf, wif[ks], ai[rt], 0, 0, 0);
;                     if (ks == ks0) ax[rt] = __builtin_amdgcn_mfma_f32_16x16x32_bf16(xf, sel, ax[rt], 0, 0, 0); } }
.Lstag_708:
.LBB0_708:
	v_mul_f32_e32 v243, 0x3fb8aa3b, v207
	s_mov_b32 s100, 0xbfb8aa3b
	v_mul_f32_e32 v211, 0xbfb8aa3b, v204
	v_mul_f32_e32 v241, 0xbfb8aa3b, v206
	v_add_u32_e32 v125, v209, v105
	v_add_u32_e32 v240, 0x11400, v125
	ds_read_b128 v[212:215], v240
	ds_read_b128 v[216:219], v240 offset:64
	ds_read_b128 v[220:223], v240 offset:128
	ds_read_b128 v[224:227], v240 offset:192
	ds_read_b128 v[228:231], v240 offset:4352
	ds_read_b128 v[232:235], v240 offset:4416
	ds_read_b128 v[236:239], v240 offset:4480
	ds_read_b128 v[244:247], v240 offset:4544
	ds_read_b128 v[248:251], v240 offset:8704
	ds_read_b128 v[252:255], v240 offset:8768
	v_mov_b32_e32 v182, v4
	v_mov_b32_e32 v179, v7
	v_mov_b32_e32 v180, v6
	v_mov_b32_e32 v181, v5
	v_mov_b32_e32 v174, v12
	v_cndmask_b32_e64 v12, 0, 1, s[36:37]
	v_mov_b32_e32 v173, v13
	v_mov_b32_e32 v175, v11
	v_mov_b32_e32 v176, v10
	v_mov_b32_e32 v177, v9
	v_mov_b32_e32 v178, v8
	s_waitcnt lgkmcnt(9)
	v_mfma_f32_16x16x32_bf16 v[8:11], v[212:215], v[36:39], 0
	v_cmp_ne_u32_e64 s[8:9], 1, v12
	s_mov_b32 s29, s28
	s_mov_b32 s30, s28
	v_mfma_f32_16x16x32_bf16 v[12:15], v[212:215], v[44:47], 0
	s_mov_b32 s31, s28
	v_mov_b64_e32 v[28:29], s[28:29]
	v_mov_b32_e32 v183, v132
	v_mov_b32_e32 v184, v131
	v_mov_b32_e32 v185, v146
	v_mov_b32_e32 v186, v145
	v_mov_b32_e32 v187, v143
	v_mov_b32_e32 v188, v133
	v_mov_b32_e32 v132, v198
	v_mov_b32_e32 v131, v200
	v_mov_b32_e32 v146, v202
	v_mov_b32_e32 v145, v203
	v_mov_b32_e32 v143, v205
	v_mov_b32_e32 v133, v124
	v_mov_b64_e32 v[30:31], s[30:31]
	s_andn2_b64 vcc, exec, s[36:37]
	s_cbranch_vccnz .LBB0_710
	v_mfma_f32_16x16x32_bf16 v[28:31], v[212:215], v[0:3], 0

; template <bool PASS2>
; __device__ __forceinline__ void lru_item(const Frame& F, const Args& a, int item) {
;     ...
;         const float ba = a.lru_ba[dir * 1536 + cg_], bi = a.lru_bi[dir * 1536 + cg_];
;         const float lam = a.lru_lambda[dir * 1536 + cg_];
;         const float logu = -8.0f * log1pf(__expf(-lam));
;         float hc = 0.f, TA = 1.f, TB = 0.f;
;         if (PASS2) { const f32x2* ag = (const f32x2*)(a.ws + WS_AGG) + ((size_t)(b * NCHUNK) * 2 + dir) * 1536 + cg_;
;             f32x2 pa[NCHUNK];
; #pragma unroll
;             for (int cc = 0; cc < NCHUNK; ++cc) pa[cc] = ag[(size_t)cc * 2 * 1536];
; #pragma unroll
;             for (int i = 0; i < NCHUNK; ++i) { const int cc = dir ? NCHUNK - 1 - i : i; const bool use = dir ? (cc > chunk) : (cc < chunk); if (use) hc = pa[cc].x * hc + pa[cc].y; } }
;         const int tstart = dir ? SEQ - 1 : 0;
;         if (dir == 1) __syncthreads();
.LBB0_744:
	s_waitcnt vmcnt(16)
	v_mul_f32_e32 v66, 0xbfb8aa3b, v70
	v_exp_f32_e32 v66, v66
	s_mov_b32 s3, 0x3f2aaaab
	s_cmp_lt_i32 s33, 14
	s_waitcnt vmcnt(0)
	v_fmac_f32_e32 v65, v64, v67
	v_add_f32_e32 v70, 1.0, v66
	v_frexp_mant_f32_e32 v72, v70
	v_cvt_f64_f32_e32 v[68:69], v70
	v_add_f32_e32 v71, -1.0, v70
	v_frexp_exp_i32_f64_e32 v68, v[68:69]
	v_cmp_gt_f32_e32 vcc, s3, v72
	v_sub_f32_e32 v73, v71, v70
	v_sub_f32_e32 v71, v66, v71
	v_subbrev_co_u32_e32 v68, vcc, 0, v68, vcc
	v_add_f32_e32 v73, 1.0, v73
	v_sub_u32_e32 v69, 0, v68
	v_add_f32_e32 v71, v71, v73
	v_ldexp_f32 v70, v70, v69
	v_ldexp_f32 v69, v71, v69
	v_add_f32_e32 v71, -1.0, v70
	v_add_f32_e32 v74, 1.0, v70
	v_add_f32_e32 v72, 1.0, v71
	v_add_f32_e32 v75, -1.0, v74
	v_sub_f32_e32 v72, v70, v72
	v_sub_f32_e32 v70, v70, v75
	v_add_f32_e32 v72, v69, v72
	v_add_f32_e32 v69, v69, v70
	v_add_f32_e32 v70, v74, v69
	v_rcp_f32_e32 v75, v70
	v_add_f32_e32 v73, v71, v72
	v_sub_f32_e32 v71, v73, v71
	v_sub_f32_e32 v71, v72, v71
	v_sub_f32_e32 v72, v70, v74
	v_sub_f32_e32 v69, v69, v72
	v_mul_f32_e32 v72, v73, v75
	v_mul_f32_e32 v74, v70, v72
	v_fma_f32 v76, v72, v70, -v74
	v_fmac_f32_e32 v76, v72, v69
	v_add_f32_e32 v77, v74, v76
	v_sub_f32_e32 v78, v73, v77
	v_sub_f32_e32 v73, v73, v78
	v_sub_f32_e32 v74, v77, v74
	v_sub_f32_e32 v73, v73, v77
	v_add_f32_e32 v71, v71, v73
	v_sub_f32_e32 v73, v74, v76
	v_add_f32_e32 v71, v73, v71
	v_add_f32_e32 v73, v78, v71
	v_mul_f32_e32 v74, v75, v73
	v_mul_f32_e32 v76, v70, v74
	v_fma_f32 v70, v74, v70, -v76
	v_fmac_f32_e32 v70, v74, v69
	v_sub_f32_e32 v69, v78, v73
	v_add_f32_e32 v69, v71, v69
	v_add_f32_e32 v71, v76, v70
	v_sub_f32_e32 v77, v73, v71
	v_sub_f32_e32 v73, v73, v77
	v_sub_f32_e32 v76, v71, v76
	v_sub_f32_e32 v71, v73, v71
	v_add_f32_e32 v69, v69, v71
	v_sub_f32_e32 v70, v76, v70
	v_cvt_f32_i32_e32 v68, v68
	v_add_f32_e32 v69, v70, v69
	v_add_f32_e32 v70, v72, v74
	v_add_f32_e32 v69, v77, v69
	v_sub_f32_e32 v71, v70, v72
	v_mul_f32_e32 v69, v75, v69
	v_sub_f32_e32 v71, v74, v71
	v_add_f32_e32 v69, v71, v69
	v_mul_f32_e32 v74, 0x3f317218, v68
	s_mov_b32 s3, 0x3f317218
	v_add_f32_e32 v71, v70, v69
	v_fma_f32 v75, v68, s3, -v74
	v_mul_f32_e32 v72, v71, v71
	v_fmac_f32_e32 v75, 0xb102e308, v68
	v_sub_f32_e32 v68, v71, v70
	v_fmamk_f32 v73, v72, 0x3e9b6dac, v134
	v_sub_f32_e32 v68, v69, v68
	v_add_f32_e32 v69, v74, v75
	v_fmaak_f32 v73, v72, v73, 0x3f2aaada
	v_sub_f32_e32 v70, v69, v74
	v_ldexp_f32 v74, v71, 1
	v_mul_f32_e32 v71, v71, v72
	v_mul_f32_e32 v71, v71, v73
	v_add_f32_e32 v72, v74, v71
	v_sub_f32_e32 v73, v72, v74
	v_ldexp_f32 v68, v68, 1
	v_sub_f32_e32 v71, v71, v73
	v_add_f32_e32 v68, v68, v71
	v_add_f32_e32 v71, v72, v68
	v_sub_f32_e32 v72, v71, v72
	v_sub_f32_e32 v68, v68, v72
	v_add_f32_e32 v72, v69, v71
	v_sub_f32_e32 v73, v72, v69
	v_sub_f32_e32 v74, v72, v73
	v_sub_f32_e32 v70, v75, v70
	v_sub_f32_e32 v69, v69, v74
	v_sub_f32_e32 v71, v71, v73
	v_add_f32_e32 v69, v71, v69
	v_add_f32_e32 v71, v70, v68
	v_sub_f32_e32 v73, v71, v70
	v_sub_f32_e32 v74, v71, v73
	v_sub_f32_e32 v70, v70, v74
	v_sub_f32_e32 v68, v68, v73
	v_add_f32_e32 v69, v71, v69
	v_add_f32_e32 v68, v68, v70
	v_add_f32_e32 v70, v72, v69
	v_sub_f32_e32 v71, v70, v72
	v_sub_f32_e32 v69, v69, v71
	v_add_f32_e32 v68, v68, v69
	s_mov_b32 s3, 0x7f800000
	v_add_f32_e32 v68, v70, v68
	v_cmp_neq_f32_e32 vcc, s3, v66
	s_mov_b32 s3, 0x33800000
	s_mov_b32 s2, 0
	v_cndmask_b32_e32 v68, v137, v68, vcc
	v_cmp_ngt_f32_e32 vcc, -1.0, v66
	s_barrier
	s_nop 0
	v_cndmask_b32_e32 v68, v138, v68, vcc
	v_cmp_neq_f32_e32 vcc, -1.0, v66
	s_nop 1
	v_cndmask_b32_e32 v68, v139, v68, vcc
	v_cmp_lt_f32_e64 vcc, |v66|, s3
	s_nop 1
	v_cndmask_b32_e32 v66, v68, v66, vcc
	s_cselect_b64 vcc, -1, 0
	v_cndmask_b32_e32 v64, v67, v65, vcc
	s_cmp_lt_i32 s33, 13
	v_fmac_f32_e32 v63, v62, v64
	s_cselect_b64 vcc, -1, 0
	v_cndmask_b32_e32 v62, v64, v63, vcc
	s_cmp_lt_i32 s33, 12
	v_fmac_f32_e32 v61, v60, v62
	s_cselect_b64 vcc, -1, 0
	v_cndmask_b32_e32 v60, v62, v61, vcc
	s_cmp_lt_i32 s33, 11
	v_fmac_f32_e32 v59, v58, v60
	s_cselect_b64 vcc, -1, 0
	v_cndmask_b32_e32 v58, v60, v59, vcc
	s_cmp_lt_i32 s33, 10
	v_fmac_f32_e32 v57, v56, v58
	s_cselect_b64 vcc, -1, 0
	v_cndmask_b32_e32 v56, v58, v57, vcc
	s_cmp_lt_i32 s33, 9
	v_fmac_f32_e32 v55, v54, v56
	s_cselect_b64 vcc, -1, 0
	v_cndmask_b32_e32 v54, v56, v55, vcc
	s_cmp_lt_i32 s33, 8
	v_fmac_f32_e32 v53, v52, v54
	s_cselect_b64 vcc, -1, 0
	v_cndmask_b32_e32 v52, v54, v53, vcc
	s_cmp_lt_i32 s33, 7
	v_fmac_f32_e32 v51, v50, v52
	s_cselect_b64 vcc, -1, 0
	v_cndmask_b32_e32 v50, v52, v51, vcc
	s_cmp_lt_i32 s33, 6
	v_fmac_f32_e32 v49, v48, v50
	s_cselect_b64 vcc, -1, 0
	v_cndmask_b32_e32 v48, v50, v49, vcc
	s_cmp_lt_i32 s33, 5
	v_fmac_f32_e32 v47, v46, v48
	s_cselect_b64 vcc, -1, 0
	v_cndmask_b32_e32 v46, v48, v47, vcc
	s_cmp_lt_i32 s33, 4
	v_fmac_f32_e32 v45, v44, v46
	s_cselect_b64 vcc, -1, 0
	v_cndmask_b32_e32 v44, v46, v45, vcc
	s_cmp_lt_i32 s33, 3
	v_fmac_f32_e32 v43, v42, v44
	s_cselect_b64 vcc, -1, 0
	v_cndmask_b32_e32 v42, v44, v43, vcc
	s_cmp_lt_i32 s33, 2
	v_fmac_f32_e32 v41, v40, v42
	s_cselect_b64 vcc, -1, 0
	v_cndmask_b32_e32 v40, v42, v41, vcc
	s_cmp_lt_i32 s33, 1
	v_fmac_f32_e32 v39, v38, v40
	s_cselect_b64 vcc, -1, 0
	v_cndmask_b32_e32 v38, v40, v39, vcc
	s_cmp_lt_i32 s33, 0
	v_fmac_f32_e32 v37, v36, v38
	s_cselect_b64 vcc, -1, 0
	v_cndmask_b32_e32 v127, v38, v37, vcc
	v_mul_f32_e32 v126, 0xc1000000, v66
	v_readfirstlane_b32 s98, v144
	s_cmp_lt_u32 s98, 0x100
	s_cbranch_scc1 .Lstag_746
	s_sleep 12
.Lstag_746:
	s_branch .LBB0_746

; template <bool PASS2>
; __device__ __forceinline__ void lru_item(const Frame& F, const Args& a, int item) {
;     ...
;         const float ba = a.lru_ba[dir * 1536 + cg_], bi = a.lru_bi[dir * 1536 + cg_];
;         const float lam = a.lru_lambda[dir * 1536 + cg_];
;         const float logu = -8.0f * log1pf(__expf(-lam));
;         float hc = 0.f, TA = 1.f, TB = 0.f;
;         if (PASS2) { const f32x2* ag = (const f32x2*)(a.ws + WS_AGG) + ((size_t)(b * NCHUNK) * 2 + dir) * 1536 + cg_;
;             f32x2 pa[NCHUNK];
; #pragma unroll
;             for (int cc = 0; cc < NCHUNK; ++cc) pa[cc] = ag[(size_t)cc * 2 * 1536];
; #pragma unroll
;             for (int i = 0; i < NCHUNK; ++i) { const int cc = dir ? NCHUNK - 1 - i : i; const bool use = dir ? (cc > chunk) : (cc < chunk); if (use) hc = pa[cc].x * hc + pa[cc].y; } }
;         const int tstart = dir ? SEQ - 1 : 0;
;         if (dir == 1) __syncthreads();
; #pragma unroll 1
;         for (int si = 0; si < 4; ++si) { const int s = dir ? 3 - si : si;
.LBB0_826:
	s_waitcnt vmcnt(15)
	v_mul_f32_e32 v36, 0xbfb8aa3b, v125
	v_exp_f32_e32 v36, v36
	s_cmp_gt_i32 s80, 1
	s_waitcnt vmcnt(13)
	v_fmac_f32_e32 v75, v74, v37
	s_mov_b32 s82, 0
	v_add_f32_e32 v40, 1.0, v36
	v_frexp_mant_f32_e32 v42, v40
	v_cvt_f64_f32_e32 v[38:39], v40
	v_add_f32_e32 v41, -1.0, v40
	v_frexp_exp_i32_f64_e32 v38, v[38:39]
	v_cmp_gt_f32_e32 vcc, s55, v42
	v_sub_f32_e32 v43, v41, v40
	v_sub_f32_e32 v41, v36, v41
	v_subbrev_co_u32_e32 v38, vcc, 0, v38, vcc
	v_add_f32_e32 v43, 1.0, v43
	v_sub_u32_e32 v39, 0, v38
	v_add_f32_e32 v41, v41, v43
	v_ldexp_f32 v40, v40, v39
	v_ldexp_f32 v39, v41, v39
	v_add_f32_e32 v41, -1.0, v40
	v_add_f32_e32 v44, 1.0, v40
	v_add_f32_e32 v42, 1.0, v41
	v_add_f32_e32 v45, -1.0, v44
	v_sub_f32_e32 v42, v40, v42
	v_sub_f32_e32 v40, v40, v45
	v_add_f32_e32 v42, v39, v42
	v_add_f32_e32 v39, v39, v40
	v_add_f32_e32 v40, v44, v39
	v_rcp_f32_e32 v45, v40
	v_add_f32_e32 v43, v41, v42
	v_sub_f32_e32 v41, v43, v41
	v_sub_f32_e32 v41, v42, v41
	v_sub_f32_e32 v42, v40, v44
	v_sub_f32_e32 v39, v39, v42
	v_mul_f32_e32 v42, v43, v45
	v_mul_f32_e32 v44, v40, v42
	v_fma_f32 v46, v42, v40, -v44
	v_fmac_f32_e32 v46, v42, v39
	v_add_f32_e32 v47, v44, v46
	v_sub_f32_e32 v48, v43, v47
	v_sub_f32_e32 v43, v43, v48
	v_sub_f32_e32 v44, v47, v44
	v_sub_f32_e32 v43, v43, v47
	v_add_f32_e32 v41, v41, v43
	v_sub_f32_e32 v43, v44, v46
	v_add_f32_e32 v41, v43, v41
	v_add_f32_e32 v43, v48, v41
	v_mul_f32_e32 v44, v45, v43
	v_mul_f32_e32 v46, v40, v44
	v_fma_f32 v40, v44, v40, -v46
	v_fmac_f32_e32 v40, v44, v39
	v_sub_f32_e32 v39, v48, v43
	v_add_f32_e32 v39, v41, v39
	v_add_f32_e32 v41, v46, v40
	v_sub_f32_e32 v47, v43, v41
	v_sub_f32_e32 v43, v43, v47
	v_sub_f32_e32 v46, v41, v46
	v_sub_f32_e32 v41, v43, v41
	v_add_f32_e32 v39, v39, v41
	v_sub_f32_e32 v40, v46, v40
	v_cvt_f32_i32_e32 v38, v38
	v_add_f32_e32 v39, v40, v39
	v_add_f32_e32 v40, v42, v44
	v_add_f32_e32 v39, v47, v39
	v_sub_f32_e32 v41, v40, v42
	v_mul_f32_e32 v39, v45, v39
	v_sub_f32_e32 v41, v44, v41
	v_add_f32_e32 v39, v41, v39
	v_mul_f32_e32 v44, 0x3f317218, v38
	v_add_f32_e32 v41, v40, v39
	v_fma_f32 v45, v38, s56, -v44
	v_mul_f32_e32 v42, v41, v41
	v_fmac_f32_e32 v45, 0xb102e308, v38
	v_sub_f32_e32 v38, v41, v40
	v_fmamk_f32 v43, v42, 0x3e9b6dac, v123
	v_sub_f32_e32 v38, v39, v38
	v_add_f32_e32 v39, v44, v45
	v_fmaak_f32 v43, v42, v43, 0x3f2aaada
	v_sub_f32_e32 v40, v39, v44
	v_ldexp_f32 v44, v41, 1
	v_mul_f32_e32 v41, v41, v42
	v_mul_f32_e32 v41, v41, v43
	v_add_f32_e32 v42, v44, v41
	v_sub_f32_e32 v43, v42, v44
	v_ldexp_f32 v38, v38, 1
	v_sub_f32_e32 v41, v41, v43
	v_add_f32_e32 v38, v38, v41
	v_add_f32_e32 v41, v42, v38
	v_sub_f32_e32 v42, v41, v42
	v_sub_f32_e32 v38, v38, v42
	v_add_f32_e32 v42, v39, v41
	v_sub_f32_e32 v43, v42, v39
	v_sub_f32_e32 v44, v42, v43
	v_sub_f32_e32 v40, v45, v40
	v_sub_f32_e32 v39, v39, v44
	v_sub_f32_e32 v41, v41, v43
	v_add_f32_e32 v39, v41, v39
	v_add_f32_e32 v41, v40, v38
	v_sub_f32_e32 v43, v41, v40
	v_sub_f32_e32 v44, v41, v43
	v_sub_f32_e32 v40, v40, v44
	v_sub_f32_e32 v38, v38, v43
	v_add_f32_e32 v39, v41, v39
	v_add_f32_e32 v38, v38, v40
	v_add_f32_e32 v40, v42, v39
	v_sub_f32_e32 v41, v40, v42
	v_sub_f32_e32 v39, v39, v41
	v_add_f32_e32 v38, v38, v39
	v_add_f32_e32 v38, v40, v38
	v_cmp_neq_f32_e32 vcc, s57, v36
	v_add_u32_e32 v208, s79, v103
	v_mov_b32_e32 v209, v121
	v_cndmask_b32_e32 v38, v136, v38, vcc
	v_cmp_ngt_f32_e32 vcc, -1.0, v36
	v_mov_b32_e32 v205, 0
	v_mov_b32_e32 v203, 0
	v_cndmask_b32_e32 v38, v137, v38, vcc
	v_cmp_neq_f32_e32 vcc, -1.0, v36
	v_mov_b32_e32 v202, 0
	v_mov_b32_e32 v200, 0
	v_cndmask_b32_e32 v38, v138, v38, vcc
	v_cmp_lt_f32_e64 vcc, |v36|, s58
	v_mov_b32_e32 v198, 0
	v_mov_b32_e32 v133, 0
	v_cndmask_b32_e32 v36, v38, v36, vcc
	s_cselect_b64 vcc, -1, 0
	v_cndmask_b32_e32 v37, v37, v75, vcc
	s_cmp_gt_i32 s80, 2
	s_waitcnt vmcnt(12)
	v_fmac_f32_e32 v73, v72, v37
	s_cselect_b64 vcc, -1, 0
	v_cndmask_b32_e32 v37, v37, v73, vcc
	s_cmp_gt_i32 s80, 3
	s_waitcnt vmcnt(11)
	v_fmac_f32_e32 v69, v68, v37
	s_cselect_b64 vcc, -1, 0
	v_cndmask_b32_e32 v37, v37, v69, vcc
	s_cmp_gt_i32 s80, 4
	s_waitcnt vmcnt(10)
	v_fmac_f32_e32 v71, v70, v37
	s_cselect_b64 vcc, -1, 0
	v_cndmask_b32_e32 v37, v37, v71, vcc
	s_cmp_gt_i32 s80, 5
	s_waitcnt vmcnt(9)
	v_fmac_f32_e32 v83, v82, v37
	s_cselect_b64 vcc, -1, 0
	v_cndmask_b32_e32 v37, v37, v83, vcc
	s_cmp_gt_i32 s80, 6
	s_waitcnt vmcnt(8)
	v_fmac_f32_e32 v81, v80, v37
	s_cselect_b64 vcc, -1, 0
	v_cndmask_b32_e32 v37, v37, v81, vcc
	s_cmp_gt_i32 s80, 7
	s_waitcnt vmcnt(7)
	v_fmac_f32_e32 v77, v76, v37
	s_cselect_b64 vcc, -1, 0
	v_cndmask_b32_e32 v37, v37, v77, vcc
	s_cmp_gt_i32 s80, 8
	s_waitcnt vmcnt(6)
	v_fmac_f32_e32 v79, v78, v37
	s_cselect_b64 vcc, -1, 0
	v_cndmask_b32_e32 v37, v37, v79, vcc
	s_cmp_gt_i32 s80, 9
	s_waitcnt vmcnt(5)
	v_fmac_f32_e32 v91, v90, v37
	s_cselect_b64 vcc, -1, 0
	v_cndmask_b32_e32 v37, v37, v91, vcc
	s_cmp_gt_i32 s80, 10
	s_waitcnt vmcnt(4)
	v_fmac_f32_e32 v89, v88, v37
	s_cselect_b64 vcc, -1, 0
	v_cndmask_b32_e32 v37, v37, v89, vcc
	s_cmp_gt_i32 s80, 11
	s_waitcnt vmcnt(3)
	v_fmac_f32_e32 v85, v84, v37
	s_cselect_b64 vcc, -1, 0
	v_cndmask_b32_e32 v37, v37, v85, vcc
	s_cmp_gt_i32 s80, 12
	s_waitcnt vmcnt(2)
	v_fmac_f32_e32 v87, v86, v37
	s_cselect_b64 vcc, -1, 0
	v_cndmask_b32_e32 v37, v37, v87, vcc
	s_cmp_gt_i32 s80, 13
	s_waitcnt vmcnt(1)
	v_fmac_f32_e32 v131, v130, v37
	s_cselect_b64 vcc, -1, 0
	v_cndmask_b32_e32 v37, v37, v131, vcc
	s_cmp_gt_i32 s80, 14
	s_waitcnt vmcnt(0)
	v_fmac_f32_e32 v129, v128, v37
	s_cselect_b64 vcc, -1, 0
	v_cndmask_b32_e32 v210, v37, v129, vcc
	v_mul_f32_e32 v207, 0xc1000000, v36
	v_or_b32_e32 v128, 64, v139
	v_or_b32_e32 v129, 0x80, v139
	v_or_b32_e32 v130, 0xc0, v139
	v_mov_b32_e32 v142, 0
	v_mov_b32_e32 v143, 0
	v_mov_b32_e32 v146, 0
	v_mov_b32_e32 v131, 0
	v_mov_b32_e32 v132, 0
	v_mov_b32_e32 v36, 0
	v_mov_b32_e32 v37, 0
	v_mov_b32_e32 v38, 0
	v_mov_b32_e32 v39, 0
	v_mov_b32_e32 v40, 0
	v_mov_b32_e32 v41, 0
	v_mov_b32_e32 v42, 0
	v_mov_b32_e32 v43, 0
	v_mov_b32_e32 v44, 0
	v_mov_b32_e32 v45, 0
	v_mov_b32_e32 v147, 0
	v_mov_b32_e32 v148, 0
	v_mov_b32_e32 v149, 0
	v_mov_b32_e32 v150, 0
	v_mov_b32_e32 v151, 0
	v_mov_b32_e32 v152, 0
	v_mov_b32_e32 v153, 0
	v_mov_b32_e32 v154, 0
	v_mov_b32_e32 v155, 0
	v_mov_b32_e32 v156, 0
	v_mov_b32_e32 v157, 0
	v_mov_b32_e32 v158, 0
	v_mov_b32_e32 v159, 0
	v_mov_b32_e32 v160, 0
	v_mov_b32_e32 v161, 0
	v_mov_b32_e32 v162, 0
	v_mov_b32_e32 v163, 0
	v_mov_b32_e32 v164, 0
	v_mov_b32_e32 v165, 0
	v_mov_b32_e32 v166, 0
	v_mov_b32_e32 v167, 0
	v_mov_b32_e32 v168, 0
	v_mov_b32_e32 v169, 0
	v_mov_b32_e32 v170, 0
	v_mov_b32_e32 v171, 0
	v_mov_b32_e32 v172, 0
	v_readfirstlane_b32 s98, v144
	s_cmp_lt_u32 s98, 0x100
	s_cbranch_scc1 .Lstag_827
	s_sleep 12
; #define LAS __attribute__((address_space(3)))
; __device__ __forceinline__ float fsig(float x) { return __builtin_amdgcn_rcpf(1.0f + __expf(-x)); }
; template <bool PASS2>
; __device__ __forceinline__ void lru_item(const Frame& F, const Args& a, int item) {
;     ...
;         for (int si = 0; si < 4; ++si) { const int s = dir ? 3 - si : si;
;             if (PASS2 && dir == 0) {
; #pragma unroll
;                 for (int i1 = 0; i1 < 4; ++i1)
; #pragma unroll
;                     for (int i2 = 0; i2 < 4; ++i2) { hf[0][i1][i2] = hf[1][i1][i2]; hf[1][i1][i2] = hf[2][i1][i2]; hf[2][i1][i2] = hf[3][i1][i2]; } }
;             f32x4 ar[4], ai[4], ax[4];
; #pragma unroll
;             for (int rt = 0; rt < 4; ++rt) { ar[rt] = (f32x4){0.f, 0.f, 0.f, 0.f}; ai[rt] = (f32x4){0.f, 0.f, 0.f, 0.f}; ax[rt] = (f32x4){0.f, 0.f, 0.f, 0.f};
; #pragma unroll
;                 for (int ks = 0; ks < 4; ++ks) { const bf16x8 xf = *(const LAS bf16x8*)(AT + (64 * s + 16 * rt + fr) * AT_PITCH + 64 * ks + 16 * fq);
;                     ar[rt] = __builtin_amdgcn_mfma_f32_16x16x32_bf16(xf, wrf[ks], ar[rt], 0, 0, 0); ai[rt] = __builtin_amdgcn_mfma_f32_16x16x32_bf16(xf, wif[ks], ai[rt], 0, 0, 0);
;                     if (ks == ks0) ax[rt] = __builtin_amdgcn_mfma_f32_16x16x32_bf16(xf, sel, ax[rt], 0, 0, 0); } }
;             const int tl0 = 64 * s + 16 * fq;
;             float A16 = 1.f, B16 = 0.f;
; #pragma unroll
;             for (int e = 0; e < 16; ++e) { const int ee = dir ? 15 - e : e; const int rt = ee >> 2, j = ee & 3;
;                 const float rg = fsig(ar[rt][j] + ba), ig = fsig(ai[rt][j] + bi); const float la = logu * rg; const float av = __expf(la);
.Lstag_827:
.LBB0_827:
	v_mul_f32_e32 v243, 0x3fb8aa3b, v207
	s_mov_b32 s100, 0xbfb8aa3b
	v_mul_f32_e32 v211, 0xbfb8aa3b, v204
	v_mul_f32_e32 v241, 0xbfb8aa3b, v206
	v_add_u32_e32 v125, v209, v103
	v_add_u32_e32 v240, 0x11400, v125
	ds_read_b128 v[212:215], v240
	ds_read_b128 v[216:219], v240 offset:64
	ds_read_b128 v[220:223], v240 offset:128
	ds_read_b128 v[224:227], v240 offset:192
	ds_read_b128 v[228:231], v240 offset:4352
	ds_read_b128 v[232:235], v240 offset:4416
	ds_read_b128 v[236:239], v240 offset:4480
	ds_read_b128 v[244:247], v240 offset:4544
	ds_read_b128 v[248:251], v240 offset:8704
	ds_read_b128 v[252:255], v240 offset:8768
	v_mov_b32_e32 v182, v36
	v_mov_b32_e32 v179, v39
	v_mov_b32_e32 v180, v38
	v_mov_b32_e32 v181, v37
	v_mov_b32_e32 v174, v44
	v_cndmask_b32_e64 v44, 0, 1, s[2:3]
	v_mov_b32_e32 v173, v45
	v_mov_b32_e32 v175, v43
	v_mov_b32_e32 v176, v42
	v_mov_b32_e32 v177, v41
	v_mov_b32_e32 v178, v40
	s_waitcnt lgkmcnt(9)
	v_mfma_f32_16x16x32_bf16 v[40:43], v[212:215], v[4:7], 0
	v_cmp_ne_u32_e64 s[8:9], 1, v44
	s_mov_b32 s30, s28
	s_mov_b32 s31, s28
	v_mfma_f32_16x16x32_bf16 v[44:47], v[212:215], v[12:15], 0
	s_mov_b32 s29, s28
	v_mov_b64_e32 v[62:63], s[30:31]
	v_mov_b32_e32 v183, v132
	v_mov_b32_e32 v184, v131
	v_mov_b32_e32 v185, v146
	v_mov_b32_e32 v186, v143
	v_mov_b32_e32 v187, v142
	v_mov_b32_e32 v188, v133
	v_mov_b32_e32 v132, v198
	v_mov_b32_e32 v131, v200
	v_mov_b32_e32 v146, v202
	v_mov_b32_e32 v143, v203
	v_mov_b32_e32 v142, v205
	v_mov_b32_e32 v133, v124
	v_mov_b64_e32 v[60:61], s[28:29]
	s_andn2_b64 vcc, exec, s[2:3]
	s_cbranch_vccnz .LBB0_829
	v_mfma_f32_16x16x32_bf16 v[60:63], v[212:215], v[0:3], 0

; template <bool PASS2>
; __device__ __forceinline__ void lru_item(const Frame& F, const Args& a, int item) {
;     ...
;         const float ba = a.lru_ba[dir * 1536 + cg_], bi = a.lru_bi[dir * 1536 + cg_];
;         const float lam = a.lru_lambda[dir * 1536 + cg_];
;         const float logu = -8.0f * log1pf(__expf(-lam));
;         float hc = 0.f, TA = 1.f, TB = 0.f;
;         if (PASS2) { const f32x2* ag = (const f32x2*)(a.ws + WS_AGG) + ((size_t)(b * NCHUNK) * 2 + dir) * 1536 + cg_;
;             f32x2 pa[NCHUNK];
; #pragma unroll
;             for (int cc = 0; cc < NCHUNK; ++cc) pa[cc] = ag[(size_t)cc * 2 * 1536];
; #pragma unroll
;             for (int i = 0; i < NCHUNK; ++i) { const int cc = dir ? NCHUNK - 1 - i : i; const bool use = dir ? (cc > chunk) : (cc < chunk); if (use) hc = pa[cc].x * hc + pa[cc].y; } }
;         const int tstart = dir ? SEQ - 1 : 0;
;         if (dir == 1) __syncthreads();
; #pragma unroll 1
;         for (int si = 0; si < 4; ++si) { const int s = dir ? 3 - si : si;
.LBB0_863:
	s_waitcnt vmcnt(16)
	v_mul_f32_e32 v66, 0xbfb8aa3b, v70
	v_exp_f32_e32 v66, v66
	s_cmp_lt_i32 s80, 14
	s_waitcnt vmcnt(0)
	v_fmac_f32_e32 v65, v64, v67
	s_mov_b32 s46, 0
	v_add_f32_e32 v70, 1.0, v66
	v_frexp_mant_f32_e32 v72, v70
	v_cvt_f64_f32_e32 v[68:69], v70
	v_add_f32_e32 v71, -1.0, v70
	v_frexp_exp_i32_f64_e32 v68, v[68:69]
	v_cmp_gt_f32_e32 vcc, s55, v72
	v_sub_f32_e32 v73, v71, v70
	v_sub_f32_e32 v71, v66, v71
	v_subbrev_co_u32_e32 v68, vcc, 0, v68, vcc
	v_add_f32_e32 v73, 1.0, v73
	v_sub_u32_e32 v69, 0, v68
	v_add_f32_e32 v71, v71, v73
	v_ldexp_f32 v70, v70, v69
	v_ldexp_f32 v69, v71, v69
	v_add_f32_e32 v71, -1.0, v70
	v_add_f32_e32 v74, 1.0, v70
	v_add_f32_e32 v72, 1.0, v71
	v_add_f32_e32 v75, -1.0, v74
	v_sub_f32_e32 v72, v70, v72
	v_sub_f32_e32 v70, v70, v75
	v_add_f32_e32 v72, v69, v72
	v_add_f32_e32 v69, v69, v70
	v_add_f32_e32 v70, v74, v69
	v_rcp_f32_e32 v75, v70
	v_add_f32_e32 v73, v71, v72
	v_sub_f32_e32 v71, v73, v71
	v_sub_f32_e32 v71, v72, v71
	v_sub_f32_e32 v72, v70, v74
	v_sub_f32_e32 v69, v69, v72
	v_mul_f32_e32 v72, v73, v75
	v_mul_f32_e32 v74, v70, v72
	v_fma_f32 v76, v72, v70, -v74
	v_fmac_f32_e32 v76, v72, v69
	v_add_f32_e32 v77, v74, v76
	v_sub_f32_e32 v78, v73, v77
	v_sub_f32_e32 v73, v73, v78
	v_sub_f32_e32 v74, v77, v74
	v_sub_f32_e32 v73, v73, v77
	v_add_f32_e32 v71, v71, v73
	v_sub_f32_e32 v73, v74, v76
	v_add_f32_e32 v71, v73, v71
	v_add_f32_e32 v73, v78, v71
	v_mul_f32_e32 v74, v75, v73
	v_mul_f32_e32 v76, v70, v74
	v_fma_f32 v70, v74, v70, -v76
	v_fmac_f32_e32 v70, v74, v69
	v_sub_f32_e32 v69, v78, v73
	v_add_f32_e32 v69, v71, v69
	v_add_f32_e32 v71, v76, v70
	v_sub_f32_e32 v77, v73, v71
	v_sub_f32_e32 v73, v73, v77
	v_sub_f32_e32 v76, v71, v76
	v_sub_f32_e32 v71, v73, v71
	v_add_f32_e32 v69, v69, v71
	v_sub_f32_e32 v70, v76, v70
	v_cvt_f32_i32_e32 v68, v68
	v_add_f32_e32 v69, v70, v69
	v_add_f32_e32 v70, v72, v74
	v_add_f32_e32 v69, v77, v69
	v_sub_f32_e32 v71, v70, v72
	v_mul_f32_e32 v69, v75, v69
	v_sub_f32_e32 v71, v74, v71
	v_add_f32_e32 v69, v71, v69
	v_mul_f32_e32 v74, 0x3f317218, v68
	v_add_f32_e32 v71, v70, v69
	v_fma_f32 v75, v68, s56, -v74
	v_mul_f32_e32 v72, v71, v71
	v_fmac_f32_e32 v75, 0xb102e308, v68
	v_sub_f32_e32 v68, v71, v70
	v_fmamk_f32 v73, v72, 0x3e9b6dac, v123
	v_sub_f32_e32 v68, v69, v68
	v_add_f32_e32 v69, v74, v75
	v_fmaak_f32 v73, v72, v73, 0x3f2aaada
	v_sub_f32_e32 v70, v69, v74
	v_ldexp_f32 v74, v71, 1
	v_mul_f32_e32 v71, v71, v72
	v_mul_f32_e32 v71, v71, v73
	v_add_f32_e32 v72, v74, v71
	v_sub_f32_e32 v73, v72, v74
	v_ldexp_f32 v68, v68, 1
	v_sub_f32_e32 v71, v71, v73
	v_add_f32_e32 v68, v68, v71
	v_add_f32_e32 v71, v72, v68
	v_sub_f32_e32 v72, v71, v72
	v_sub_f32_e32 v68, v68, v72
	v_add_f32_e32 v72, v69, v71
	v_sub_f32_e32 v73, v72, v69
	v_sub_f32_e32 v74, v72, v73
	v_sub_f32_e32 v70, v75, v70
	v_sub_f32_e32 v69, v69, v74
	v_sub_f32_e32 v71, v71, v73
	v_add_f32_e32 v69, v71, v69
	v_add_f32_e32 v71, v70, v68
	v_sub_f32_e32 v73, v71, v70
	v_sub_f32_e32 v74, v71, v73
	v_sub_f32_e32 v70, v70, v74
	v_sub_f32_e32 v68, v68, v73
	v_add_f32_e32 v69, v71, v69
	v_add_f32_e32 v68, v68, v70
	v_add_f32_e32 v70, v72, v69
	v_sub_f32_e32 v71, v70, v72
	v_sub_f32_e32 v69, v69, v71
	v_add_f32_e32 v68, v68, v69
	v_add_f32_e32 v68, v70, v68
	v_cmp_neq_f32_e32 vcc, s57, v66
	s_barrier
	s_nop 0
	v_cndmask_b32_e32 v68, v136, v68, vcc
	v_cmp_ngt_f32_e32 vcc, -1.0, v66
	s_nop 1
	v_cndmask_b32_e32 v68, v137, v68, vcc
	v_cmp_neq_f32_e32 vcc, -1.0, v66
	s_nop 1
	v_cndmask_b32_e32 v68, v138, v68, vcc
	v_cmp_lt_f32_e64 vcc, |v66|, s58
	s_nop 1
	v_cndmask_b32_e32 v66, v68, v66, vcc
	s_cselect_b64 vcc, -1, 0
	v_cndmask_b32_e32 v64, v67, v65, vcc
	s_cmp_lt_i32 s80, 13
	v_fmac_f32_e32 v63, v62, v64
	s_cselect_b64 vcc, -1, 0
	v_cndmask_b32_e32 v62, v64, v63, vcc
	s_cmp_lt_i32 s80, 12
	v_fmac_f32_e32 v61, v60, v62
	s_cselect_b64 vcc, -1, 0
	v_cndmask_b32_e32 v60, v62, v61, vcc
	s_cmp_lt_i32 s80, 11
	v_fmac_f32_e32 v59, v58, v60
	s_cselect_b64 vcc, -1, 0
	v_cndmask_b32_e32 v58, v60, v59, vcc
	s_cmp_lt_i32 s80, 10
	v_fmac_f32_e32 v57, v56, v58
	s_cselect_b64 vcc, -1, 0
	v_cndmask_b32_e32 v56, v58, v57, vcc
	s_cmp_lt_i32 s80, 9
	v_fmac_f32_e32 v55, v54, v56
	s_cselect_b64 vcc, -1, 0
	v_cndmask_b32_e32 v54, v56, v55, vcc
	s_cmp_lt_i32 s80, 8
	v_fmac_f32_e32 v53, v52, v54
	s_cselect_b64 vcc, -1, 0
	v_cndmask_b32_e32 v52, v54, v53, vcc
	s_cmp_lt_i32 s80, 7
	v_fmac_f32_e32 v51, v50, v52
	s_cselect_b64 vcc, -1, 0
	v_cndmask_b32_e32 v50, v52, v51, vcc
	s_cmp_lt_i32 s80, 6
	v_fmac_f32_e32 v49, v48, v50
	s_cselect_b64 vcc, -1, 0
	v_cndmask_b32_e32 v48, v50, v49, vcc
	s_cmp_lt_i32 s80, 5
	v_fmac_f32_e32 v47, v46, v48
	s_cselect_b64 vcc, -1, 0
	v_cndmask_b32_e32 v46, v48, v47, vcc
	s_cmp_lt_i32 s80, 4
	v_fmac_f32_e32 v45, v44, v46
	s_cselect_b64 vcc, -1, 0
	v_cndmask_b32_e32 v44, v46, v45, vcc
	s_cmp_lt_i32 s80, 3
	v_fmac_f32_e32 v43, v42, v44
	s_cselect_b64 vcc, -1, 0
	v_cndmask_b32_e32 v42, v44, v43, vcc
	s_cmp_lt_i32 s80, 2
	v_fmac_f32_e32 v41, v40, v42
	s_cselect_b64 vcc, -1, 0
	v_cndmask_b32_e32 v40, v42, v41, vcc
	s_cmp_lt_i32 s80, 1
	v_fmac_f32_e32 v39, v38, v40
	s_cselect_b64 vcc, -1, 0
	v_cndmask_b32_e32 v38, v40, v39, vcc
	s_cmp_lt_i32 s80, 0
	v_fmac_f32_e32 v37, v36, v38
	s_cselect_b64 vcc, -1, 0
	v_cndmask_b32_e32 v127, v38, v37, vcc
	v_mul_f32_e32 v126, 0xc1000000, v66
	v_readfirstlane_b32 s98, v144
	s_cmp_lt_u32 s98, 0x100
	s_cbranch_scc1 .Lstag_865
	s_sleep 12
